# speedup vs baseline: 1.0107x; 1.0022x over previous
.LBB0_27:
	s_add_u32 s58, s24, 0xfffc0080
	s_addc_u32 s59, s25, -1
	s_add_i32 s80, 0, 0x10000
	s_cmp_eq_u32 s84, 12
	s_cselect_b32 s61, s18, s59
	s_cselect_b32 s60, s19, s58
	v_add_u32_e32 v128, s80, v209
	s_cselect_b32 s59, s13, s77
	s_cselect_b32 s58, s53, s76
	s_add_i32 s81, 0, 0x14000
	ds_read_b128 v[130:133], v128
	ds_read_b128 v[134:137], v128 offset:1024
	ds_read_b128 v[138:141], v128 offset:2048
	ds_read_b128 v[142:145], v128 offset:3072
	v_add_u32_e32 v128, s81, v209
	ds_read_b128 v[146:149], v128
	ds_read_b128 v[150:153], v128 offset:1024
	ds_read_b128 v[154:157], v128 offset:2048
	ds_read_b128 v[158:161], v128 offset:3072
	s_add_i32 m0, s16, 0xc000
	ds_read_b128 v[162:165], v211
	ds_read_b128 v[166:169], v211 offset:1024
	ds_read_b128 v[170:173], v211 offset:2048
	ds_read_b128 v[174:177], v211 offset:3072
	ds_read_b128 v[178:181], v211 offset:4096
	ds_read_b128 v[182:185], v211 offset:5120
	ds_read_b128 v[212:215], v211 offset:6144
	ds_read_b128 v[216:219], v211 offset:7168
	global_load_lds_dwordx4 v202, s[24:25]
	s_add_i32 m0, s16, 0xe000
	s_nop 0
	global_load_lds_dwordx4 v204, s[24:25]
	s_waitcnt vmcnt(8)
	s_waitcnt lgkmcnt(0)
	s_barrier
	s_setprio 1
	s_waitcnt lgkmcnt(0)
	v_mfma_f32_16x16x32_bf16 v[124:127], v[130:133], v[162:165], v[124:127]
	v_mfma_f32_16x16x32_bf16 v[120:123], v[138:141], v[162:165], v[120:123]
	v_mfma_f32_16x16x32_bf16 v[116:119], v[130:133], v[170:173], v[116:119]
	v_mfma_f32_16x16x32_bf16 v[112:115], v[138:141], v[170:173], v[112:115]
	v_mfma_f32_16x16x32_bf16 v[108:111], v[130:133], v[178:181], v[108:111]
	v_mfma_f32_16x16x32_bf16 v[104:107], v[138:141], v[178:181], v[104:107]
	v_mfma_f32_16x16x32_bf16 v[100:103], v[130:133], v[212:215], v[100:103]
	v_mfma_f32_16x16x32_bf16 v[96:99], v[138:141], v[212:215], v[96:99]
	v_mfma_f32_16x16x32_bf16 v[124:127], v[134:137], v[166:169], v[124:127]
	v_mfma_f32_16x16x32_bf16 v[120:123], v[142:145], v[166:169], v[120:123]
	v_mfma_f32_16x16x32_bf16 v[116:119], v[134:137], v[174:177], v[116:119]
	v_mfma_f32_16x16x32_bf16 v[112:115], v[142:145], v[174:177], v[112:115]
	v_mfma_f32_16x16x32_bf16 v[108:111], v[134:137], v[182:185], v[108:111]
	v_mfma_f32_16x16x32_bf16 v[104:107], v[142:145], v[182:185], v[104:107]
	v_mfma_f32_16x16x32_bf16 v[100:103], v[134:137], v[216:219], v[100:103]
	v_mfma_f32_16x16x32_bf16 v[96:99], v[142:145], v[216:219], v[96:99]
	s_setprio 0
	s_setprio 1
	v_mfma_f32_16x16x32_bf16 v[92:95], v[146:149], v[162:165], v[92:95]
	v_mfma_f32_16x16x32_bf16 v[88:91], v[154:157], v[162:165], v[88:91]
	v_mfma_f32_16x16x32_bf16 v[84:87], v[146:149], v[170:173], v[84:87]
	v_mfma_f32_16x16x32_bf16 v[80:83], v[154:157], v[170:173], v[80:83]
	v_mfma_f32_16x16x32_bf16 v[76:79], v[146:149], v[178:181], v[76:79]
	v_mfma_f32_16x16x32_bf16 v[72:75], v[154:157], v[178:181], v[72:75]
	v_mfma_f32_16x16x32_bf16 v[68:71], v[146:149], v[212:215], v[68:71]
	v_mfma_f32_16x16x32_bf16 v[64:67], v[154:157], v[212:215], v[64:67]
	v_mfma_f32_16x16x32_bf16 v[92:95], v[150:153], v[166:169], v[92:95]
	v_mfma_f32_16x16x32_bf16 v[88:91], v[158:161], v[166:169], v[88:91]
	v_mfma_f32_16x16x32_bf16 v[84:87], v[150:153], v[174:177], v[84:87]
	v_mfma_f32_16x16x32_bf16 v[80:83], v[158:161], v[174:177], v[80:83]
	v_mfma_f32_16x16x32_bf16 v[76:79], v[150:153], v[182:185], v[76:79]
	v_mfma_f32_16x16x32_bf16 v[72:75], v[158:161], v[182:185], v[72:75]
	v_mfma_f32_16x16x32_bf16 v[68:71], v[150:153], v[216:219], v[68:71]
	v_mfma_f32_16x16x32_bf16 v[64:67], v[158:161], v[216:219], v[64:67]
	s_setprio 0
	s_barrier
	s_add_i32 s80, s80, s33
	s_mov_b32 m0, s80
	ds_read_b128 v[162:165], v211 offset:16384
	ds_read_b128 v[166:169], v211 offset:17408
	ds_read_b128 v[170:173], v211 offset:18432
	ds_read_b128 v[174:177], v211 offset:19456
	ds_read_b128 v[178:181], v211 offset:20480
	ds_read_b128 v[182:185], v211 offset:21504
	ds_read_b128 v[212:215], v211 offset:22528
	ds_read_b128 v[216:219], v211 offset:23552
	global_load_lds_dwordx4 v196, s[58:59]
	s_add_i32 m0, s80, 0x2000
	s_add_u32 s96, s58, 0x40000
	s_addc_u32 s97, s59, 0
	s_add_i32 s80, s81, s33
	global_load_lds_dwordx4 v192, s[58:59]
	s_mov_b32 m0, s80
	s_nop 0
	global_load_lds_dwordx4 v196, s[96:97]
	s_add_i32 m0, s80, 0x2000
	s_nop 0
	global_load_lds_dwordx4 v192, s[96:97]
	s_mov_b32 m0, s16
	s_nop 0
	global_load_lds_dwordx4 v198, s[60:61]
	s_mov_b32 m0, s17
	s_nop 0
	global_load_lds_dwordx4 v194, s[60:61]
	s_add_u32 s100, s60, 0x80
	s_addc_u32 s101, s61, 0
	s_waitcnt vmcnt(8)
	s_waitcnt lgkmcnt(0)
	s_barrier
	s_setprio 1
	s_waitcnt lgkmcnt(0)
	v_mfma_f32_16x16x32_bf16 v[60:63], v[130:133], v[162:165], v[60:63]
	v_mfma_f32_16x16x32_bf16 v[56:59], v[138:141], v[162:165], v[56:59]
	v_mfma_f32_16x16x32_bf16 v[52:55], v[130:133], v[170:173], v[52:55]
	v_mfma_f32_16x16x32_bf16 v[48:51], v[138:141], v[170:173], v[48:51]
	v_mfma_f32_16x16x32_bf16 v[44:47], v[130:133], v[178:181], v[44:47]
	v_mfma_f32_16x16x32_bf16 v[40:43], v[138:141], v[178:181], v[40:43]
	v_mfma_f32_16x16x32_bf16 v[36:39], v[130:133], v[212:215], v[36:39]
	v_mfma_f32_16x16x32_bf16 v[32:35], v[138:141], v[212:215], v[32:35]
	v_mfma_f32_16x16x32_bf16 v[60:63], v[134:137], v[166:169], v[60:63]
	v_mfma_f32_16x16x32_bf16 v[56:59], v[142:145], v[166:169], v[56:59]
	v_mfma_f32_16x16x32_bf16 v[52:55], v[134:137], v[174:177], v[52:55]
	v_mfma_f32_16x16x32_bf16 v[48:51], v[142:145], v[174:177], v[48:51]
	v_mfma_f32_16x16x32_bf16 v[44:47], v[134:137], v[182:185], v[44:47]
	v_mfma_f32_16x16x32_bf16 v[40:43], v[142:145], v[182:185], v[40:43]
	v_mfma_f32_16x16x32_bf16 v[36:39], v[134:137], v[216:219], v[36:39]
	v_mfma_f32_16x16x32_bf16 v[32:35], v[142:145], v[216:219], v[32:35]
	s_setprio 0
	s_setprio 1
	v_mfma_f32_16x16x32_bf16 v[28:31], v[146:149], v[162:165], v[28:31]
	v_mfma_f32_16x16x32_bf16 v[24:27], v[154:157], v[162:165], v[24:27]
	v_mfma_f32_16x16x32_bf16 v[20:23], v[146:149], v[170:173], v[20:23]
	v_mfma_f32_16x16x32_bf16 v[16:19], v[154:157], v[170:173], v[16:19]
	v_mfma_f32_16x16x32_bf16 v[12:15], v[146:149], v[178:181], v[12:15]
	v_mfma_f32_16x16x32_bf16 v[8:11], v[154:157], v[178:181], v[8:11]
	v_mfma_f32_16x16x32_bf16 v[4:7], v[146:149], v[212:215], v[4:7]
	v_mfma_f32_16x16x32_bf16 v[0:3], v[154:157], v[212:215], v[0:3]
	v_mfma_f32_16x16x32_bf16 v[28:31], v[150:153], v[166:169], v[28:31]
	v_mfma_f32_16x16x32_bf16 v[24:27], v[158:161], v[166:169], v[24:27]
	v_mfma_f32_16x16x32_bf16 v[20:23], v[150:153], v[174:177], v[20:23]
	v_mfma_f32_16x16x32_bf16 v[16:19], v[158:161], v[174:177], v[16:19]
	v_mfma_f32_16x16x32_bf16 v[12:15], v[150:153], v[182:185], v[12:15]
	v_mfma_f32_16x16x32_bf16 v[8:11], v[158:161], v[182:185], v[8:11]
	v_mfma_f32_16x16x32_bf16 v[4:7], v[150:153], v[216:219], v[4:7]
	v_mfma_f32_16x16x32_bf16 v[0:3], v[158:161], v[216:219], v[0:3]
	s_setprio 0
	s_barrier
	s_add_i32 s80, 0, 0x18000
	v_add_u32_e32 v128, s80, v209
	s_add_i32 s81, 0, 0x1c000
	ds_read_b128 v[130:133], v128
	ds_read_b128 v[134:137], v128 offset:1024
	ds_read_b128 v[138:141], v128 offset:2048
	ds_read_b128 v[142:145], v128 offset:3072
	v_add_u32_e32 v128, s81, v209
	ds_read_b128 v[146:149], v128
	ds_read_b128 v[150:153], v128 offset:1024
	ds_read_b128 v[154:157], v128 offset:2048
	ds_read_b128 v[158:161], v128 offset:3072
	s_add_u32 s60, s60, 0x40000
	s_addc_u32 s61, s61, 0
	s_mov_b32 m0, s23
	ds_read_b128 v[162:165], v211 offset:32768
	ds_read_b128 v[166:169], v211 offset:33792
	ds_read_b128 v[170:173], v211 offset:34816
	ds_read_b128 v[174:177], v211 offset:35840
	ds_read_b128 v[178:181], v211 offset:36864
	ds_read_b128 v[182:185], v211 offset:37888
	ds_read_b128 v[212:215], v211 offset:38912
	ds_read_b128 v[216:219], v211 offset:39936
	global_load_lds_dwordx4 v198, s[60:61]
	s_mov_b32 m0, s44
	s_nop 0
	global_load_lds_dwordx4 v194, s[60:61]
	s_waitcnt vmcnt(8)
	s_waitcnt lgkmcnt(0)
	s_barrier
	s_setprio 1
	s_waitcnt lgkmcnt(0)
	v_mfma_f32_16x16x32_bf16 v[124:127], v[130:133], v[162:165], v[124:127]
	v_mfma_f32_16x16x32_bf16 v[120:123], v[138:141], v[162:165], v[120:123]
	v_mfma_f32_16x16x32_bf16 v[116:119], v[130:133], v[170:173], v[116:119]
	v_mfma_f32_16x16x32_bf16 v[112:115], v[138:141], v[170:173], v[112:115]
	v_mfma_f32_16x16x32_bf16 v[108:111], v[130:133], v[178:181], v[108:111]
	v_mfma_f32_16x16x32_bf16 v[104:107], v[138:141], v[178:181], v[104:107]
	v_mfma_f32_16x16x32_bf16 v[100:103], v[130:133], v[212:215], v[100:103]
	v_mfma_f32_16x16x32_bf16 v[96:99], v[138:141], v[212:215], v[96:99]
	v_mfma_f32_16x16x32_bf16 v[124:127], v[134:137], v[166:169], v[124:127]
	v_mfma_f32_16x16x32_bf16 v[120:123], v[142:145], v[166:169], v[120:123]
	v_mfma_f32_16x16x32_bf16 v[116:119], v[134:137], v[174:177], v[116:119]
	v_mfma_f32_16x16x32_bf16 v[112:115], v[142:145], v[174:177], v[112:115]
	v_mfma_f32_16x16x32_bf16 v[108:111], v[134:137], v[182:185], v[108:111]
	v_mfma_f32_16x16x32_bf16 v[104:107], v[142:145], v[182:185], v[104:107]
	v_mfma_f32_16x16x32_bf16 v[100:103], v[134:137], v[216:219], v[100:103]
	v_mfma_f32_16x16x32_bf16 v[96:99], v[142:145], v[216:219], v[96:99]
	s_setprio 0
	s_setprio 1
	v_mfma_f32_16x16x32_bf16 v[92:95], v[146:149], v[162:165], v[92:95]
	v_mfma_f32_16x16x32_bf16 v[88:91], v[154:157], v[162:165], v[88:91]
	v_mfma_f32_16x16x32_bf16 v[84:87], v[146:149], v[170:173], v[84:87]
	v_mfma_f32_16x16x32_bf16 v[80:83], v[154:157], v[170:173], v[80:83]
	v_mfma_f32_16x16x32_bf16 v[76:79], v[146:149], v[178:181], v[76:79]
	v_mfma_f32_16x16x32_bf16 v[72:75], v[154:157], v[178:181], v[72:75]
	v_mfma_f32_16x16x32_bf16 v[68:71], v[146:149], v[212:215], v[68:71]
	v_mfma_f32_16x16x32_bf16 v[64:67], v[154:157], v[212:215], v[64:67]
	v_mfma_f32_16x16x32_bf16 v[92:95], v[150:153], v[166:169], v[92:95]
	v_mfma_f32_16x16x32_bf16 v[88:91], v[158:161], v[166:169], v[88:91]
	v_mfma_f32_16x16x32_bf16 v[84:87], v[150:153], v[174:177], v[84:87]
	v_mfma_f32_16x16x32_bf16 v[80:83], v[158:161], v[174:177], v[80:83]
	v_mfma_f32_16x16x32_bf16 v[76:79], v[150:153], v[182:185], v[76:79]
	v_mfma_f32_16x16x32_bf16 v[72:75], v[158:161], v[182:185], v[72:75]
	v_mfma_f32_16x16x32_bf16 v[68:71], v[150:153], v[216:219], v[68:71]
	v_mfma_f32_16x16x32_bf16 v[64:67], v[158:161], v[216:219], v[64:67]
	s_setprio 0
	s_barrier
	s_add_i32 s60, s80, s33
	s_add_u32 s58, s58, 0x80
	s_addc_u32 s59, s59, 0
	s_mov_b32 m0, s60
	ds_read_b128 v[162:165], v211 offset:49152
	ds_read_b128 v[166:169], v211 offset:50176
	ds_read_b128 v[170:173], v211 offset:51200
	ds_read_b128 v[174:177], v211 offset:52224
	ds_read_b128 v[178:181], v211 offset:53248
	ds_read_b128 v[182:185], v211 offset:54272
	ds_read_b128 v[212:215], v211 offset:55296
	ds_read_b128 v[216:219], v211 offset:56320
	global_load_lds_dwordx4 v196, s[58:59]
	s_add_i32 m0, s60, 0x2000
	s_add_i32 s60, s81, s33
	global_load_lds_dwordx4 v192, s[58:59]
	s_add_u32 s58, s58, 0x40000
	s_addc_u32 s59, s59, 0
	s_mov_b32 m0, s60
	s_nop 0
	global_load_lds_dwordx4 v196, s[58:59]
	s_add_i32 m0, s60, 0x2000
	s_nop 0
	global_load_lds_dwordx4 v192, s[58:59]
	s_mov_b32 m0, s63
	s_nop 0
	global_load_lds_dwordx4 v198, s[100:101]
	s_mov_b32 m0, s64
	s_nop 0
	global_load_lds_dwordx4 v194, s[100:101]
	s_waitcnt vmcnt(8)
	s_waitcnt lgkmcnt(0)
	s_barrier
	s_setprio 1
	s_waitcnt lgkmcnt(0)
	v_mfma_f32_16x16x32_bf16 v[60:63], v[130:133], v[162:165], v[60:63]
	v_mfma_f32_16x16x32_bf16 v[56:59], v[138:141], v[162:165], v[56:59]
	v_mfma_f32_16x16x32_bf16 v[52:55], v[130:133], v[170:173], v[52:55]
	v_mfma_f32_16x16x32_bf16 v[48:51], v[138:141], v[170:173], v[48:51]
	v_mfma_f32_16x16x32_bf16 v[44:47], v[130:133], v[178:181], v[44:47]
	v_mfma_f32_16x16x32_bf16 v[40:43], v[138:141], v[178:181], v[40:43]
	v_mfma_f32_16x16x32_bf16 v[36:39], v[130:133], v[212:215], v[36:39]
	v_mfma_f32_16x16x32_bf16 v[32:35], v[138:141], v[212:215], v[32:35]
	v_mfma_f32_16x16x32_bf16 v[60:63], v[134:137], v[166:169], v[60:63]
	v_mfma_f32_16x16x32_bf16 v[56:59], v[142:145], v[166:169], v[56:59]
	v_mfma_f32_16x16x32_bf16 v[52:55], v[134:137], v[174:177], v[52:55]
	v_mfma_f32_16x16x32_bf16 v[48:51], v[142:145], v[174:177], v[48:51]
	v_mfma_f32_16x16x32_bf16 v[44:47], v[134:137], v[182:185], v[44:47]
	v_mfma_f32_16x16x32_bf16 v[40:43], v[142:145], v[182:185], v[40:43]
	v_mfma_f32_16x16x32_bf16 v[36:39], v[134:137], v[216:219], v[36:39]
	v_mfma_f32_16x16x32_bf16 v[32:35], v[142:145], v[216:219], v[32:35]
	s_setprio 0
	s_setprio 1
	v_mfma_f32_16x16x32_bf16 v[28:31], v[146:149], v[162:165], v[28:31]
	v_mfma_f32_16x16x32_bf16 v[24:27], v[154:157], v[162:165], v[24:27]
	v_mfma_f32_16x16x32_bf16 v[20:23], v[146:149], v[170:173], v[20:23]
	v_mfma_f32_16x16x32_bf16 v[16:19], v[154:157], v[170:173], v[16:19]
	v_mfma_f32_16x16x32_bf16 v[12:15], v[146:149], v[178:181], v[12:15]
	v_mfma_f32_16x16x32_bf16 v[8:11], v[154:157], v[178:181], v[8:11]
	v_mfma_f32_16x16x32_bf16 v[4:7], v[146:149], v[212:215], v[4:7]
	v_mfma_f32_16x16x32_bf16 v[0:3], v[154:157], v[212:215], v[0:3]
	v_mfma_f32_16x16x32_bf16 v[28:31], v[150:153], v[166:169], v[28:31]
	v_mfma_f32_16x16x32_bf16 v[24:27], v[158:161], v[166:169], v[24:27]
	v_mfma_f32_16x16x32_bf16 v[20:23], v[150:153], v[174:177], v[20:23]
	v_mfma_f32_16x16x32_bf16 v[16:19], v[158:161], v[174:177], v[16:19]
	v_mfma_f32_16x16x32_bf16 v[12:15], v[150:153], v[182:185], v[12:15]
	v_mfma_f32_16x16x32_bf16 v[8:11], v[158:161], v[182:185], v[8:11]
	v_mfma_f32_16x16x32_bf16 v[4:7], v[150:153], v[216:219], v[4:7]
	v_mfma_f32_16x16x32_bf16 v[0:3], v[158:161], v[216:219], v[0:3]
	s_setprio 0
	s_barrier
	s_add_i32 s84, s84, 2
	s_add_u32 s24, s24, 0x100
	s_addc_u32 s25, s25, 0
	s_add_u32 s76, s76, 0x100
	s_addc_u32 s77, s77, 0
	s_cmp_gt_u32 s84, 13
	s_cbranch_scc0 .LBB0_27
	s_and_b64 vcc, exec, s[10:11]
	s_cbranch_vccz .LBB0_30
	s_barrier

.LBB0_114:
	s_add_u32 s20, s0, 0xfff80080
	s_addc_u32 s66, s1, -1
	s_add_i32 s80, 0, 0x10000
	s_cmp_eq_u32 s90, 28
	s_cselect_b32 s97, s3, s66
	s_cselect_b32 s96, s13, s20
	v_add_u32_e32 v128, s80, v174
	s_cselect_b32 s67, s18, s61
	s_cselect_b32 s66, s19, s59
	s_add_i32 s20, 0, 0x14000
	ds_read_b128 v[130:133], v128
	ds_read_b128 v[134:137], v128 offset:1024
	ds_read_b128 v[152:155], v128 offset:2048
	ds_read_b128 v[156:159], v128 offset:3072
	v_add_u32_e32 v128, s20, v174
	ds_read_b128 v[160:163], v128
	ds_read_b128 v[164:167], v128 offset:1024
	ds_read_b128 v[168:171], v128 offset:2048
	ds_read_b128 v[178:181], v128 offset:3072
	s_add_i32 m0, s25, 0xc000
	ds_read_b128 v[182:185], v176
	ds_read_b128 v[192:195], v176 offset:1024
	ds_read_b128 v[196:199], v176 offset:2048
	ds_read_b128 v[200:203], v176 offset:3072
	ds_read_b128 v[204:207], v176 offset:4096
	ds_read_b128 v[208:211], v176 offset:5120
	ds_read_b128 v[212:215], v176 offset:6144
	ds_read_b128 v[216:219], v176 offset:7168
	global_load_lds_dwordx4 v148, s[0:1]
	s_add_i32 m0, s25, 0xe000
	s_nop 0
	global_load_lds_dwordx4 v150, s[0:1]
	s_waitcnt vmcnt(8)
	s_waitcnt lgkmcnt(0)
	s_barrier
	s_setprio 1
	s_waitcnt lgkmcnt(0)
	v_mfma_f32_16x16x32_bf16 v[124:127], v[130:133], v[182:185], v[124:127]
	v_mfma_f32_16x16x32_bf16 v[120:123], v[152:155], v[182:185], v[120:123]
	v_mfma_f32_16x16x32_bf16 v[108:111], v[130:133], v[196:199], v[108:111]
	v_mfma_f32_16x16x32_bf16 v[104:107], v[152:155], v[196:199], v[104:107]
	v_mfma_f32_16x16x32_bf16 v[92:95], v[130:133], v[204:207], v[92:95]
	v_mfma_f32_16x16x32_bf16 v[88:91], v[152:155], v[204:207], v[88:91]
	v_mfma_f32_16x16x32_bf16 v[76:79], v[130:133], v[212:215], v[76:79]
	v_mfma_f32_16x16x32_bf16 v[72:75], v[152:155], v[212:215], v[72:75]
	v_mfma_f32_16x16x32_bf16 v[124:127], v[134:137], v[192:195], v[124:127]
	v_mfma_f32_16x16x32_bf16 v[120:123], v[156:159], v[192:195], v[120:123]
	v_mfma_f32_16x16x32_bf16 v[108:111], v[134:137], v[200:203], v[108:111]
	v_mfma_f32_16x16x32_bf16 v[104:107], v[156:159], v[200:203], v[104:107]
	v_mfma_f32_16x16x32_bf16 v[92:95], v[134:137], v[208:211], v[92:95]
	v_mfma_f32_16x16x32_bf16 v[88:91], v[156:159], v[208:211], v[88:91]
	v_mfma_f32_16x16x32_bf16 v[76:79], v[134:137], v[216:219], v[76:79]
	v_mfma_f32_16x16x32_bf16 v[72:75], v[156:159], v[216:219], v[72:75]
	s_setprio 0
	s_setprio 1
	v_mfma_f32_16x16x32_bf16 v[116:119], v[160:163], v[182:185], v[116:119]
	v_mfma_f32_16x16x32_bf16 v[112:115], v[168:171], v[182:185], v[112:115]
	v_mfma_f32_16x16x32_bf16 v[100:103], v[160:163], v[196:199], v[100:103]
	v_mfma_f32_16x16x32_bf16 v[96:99], v[168:171], v[196:199], v[96:99]
	v_mfma_f32_16x16x32_bf16 v[84:87], v[160:163], v[204:207], v[84:87]
	v_mfma_f32_16x16x32_bf16 v[80:83], v[168:171], v[204:207], v[80:83]
	v_mfma_f32_16x16x32_bf16 v[68:71], v[160:163], v[212:215], v[68:71]
	v_mfma_f32_16x16x32_bf16 v[64:67], v[168:171], v[212:215], v[64:67]
	v_mfma_f32_16x16x32_bf16 v[116:119], v[164:167], v[192:195], v[116:119]
	v_mfma_f32_16x16x32_bf16 v[112:115], v[178:181], v[192:195], v[112:115]
	v_mfma_f32_16x16x32_bf16 v[100:103], v[164:167], v[200:203], v[100:103]
	v_mfma_f32_16x16x32_bf16 v[96:99], v[178:181], v[200:203], v[96:99]
	v_mfma_f32_16x16x32_bf16 v[84:87], v[164:167], v[208:211], v[84:87]
	v_mfma_f32_16x16x32_bf16 v[80:83], v[178:181], v[208:211], v[80:83]
	v_mfma_f32_16x16x32_bf16 v[68:71], v[164:167], v[216:219], v[68:71]
	v_mfma_f32_16x16x32_bf16 v[64:67], v[178:181], v[216:219], v[64:67]
	s_setprio 0
	s_barrier
	s_add_i32 s80, s80, s33
	s_mov_b32 m0, s80
	ds_read_b128 v[182:185], v176 offset:16384
	ds_read_b128 v[192:195], v176 offset:17408
	ds_read_b128 v[196:199], v176 offset:18432
	ds_read_b128 v[200:203], v176 offset:19456
	ds_read_b128 v[204:207], v176 offset:20480
	ds_read_b128 v[208:211], v176 offset:21504
	ds_read_b128 v[212:215], v176 offset:22528
	ds_read_b128 v[216:219], v176 offset:23552
	global_load_lds_dwordx4 v140, s[66:67]
	s_add_i32 m0, s80, 0x2000
	s_add_u32 vcc_lo, s66, 0x80000
	s_addc_u32 vcc_hi, s67, 0
	s_add_i32 s20, s20, s33
	global_load_lds_dwordx4 v144, s[66:67]
	s_mov_b32 m0, s20
	s_nop 0
	global_load_lds_dwordx4 v140, vcc
	s_add_i32 m0, s20, 0x2000
	s_nop 0
	global_load_lds_dwordx4 v144, vcc
	s_mov_b32 m0, s25
	s_nop 0
	global_load_lds_dwordx4 v138, s[96:97]
	s_mov_b32 m0, s21
	s_nop 0
	global_load_lds_dwordx4 v142, s[96:97]
	s_add_u32 s100, s96, 0x80
	s_addc_u32 s101, s97, 0
	s_waitcnt vmcnt(8)
	s_waitcnt lgkmcnt(0)
	s_barrier
	s_setprio 1
	s_waitcnt lgkmcnt(0)
	v_mfma_f32_16x16x32_bf16 v[60:63], v[130:133], v[182:185], v[60:63]
	v_mfma_f32_16x16x32_bf16 v[56:59], v[152:155], v[182:185], v[56:59]
	v_mfma_f32_16x16x32_bf16 v[44:47], v[130:133], v[196:199], v[44:47]
	v_mfma_f32_16x16x32_bf16 v[40:43], v[152:155], v[196:199], v[40:43]
	v_mfma_f32_16x16x32_bf16 v[28:31], v[130:133], v[204:207], v[28:31]
	v_mfma_f32_16x16x32_bf16 v[24:27], v[152:155], v[204:207], v[24:27]
	v_mfma_f32_16x16x32_bf16 v[12:15], v[130:133], v[212:215], v[12:15]
	v_mfma_f32_16x16x32_bf16 v[8:11], v[152:155], v[212:215], v[8:11]
	v_mfma_f32_16x16x32_bf16 v[60:63], v[134:137], v[192:195], v[60:63]
	v_mfma_f32_16x16x32_bf16 v[56:59], v[156:159], v[192:195], v[56:59]
	v_mfma_f32_16x16x32_bf16 v[44:47], v[134:137], v[200:203], v[44:47]
	v_mfma_f32_16x16x32_bf16 v[40:43], v[156:159], v[200:203], v[40:43]
	v_mfma_f32_16x16x32_bf16 v[28:31], v[134:137], v[208:211], v[28:31]
	v_mfma_f32_16x16x32_bf16 v[24:27], v[156:159], v[208:211], v[24:27]
	v_mfma_f32_16x16x32_bf16 v[12:15], v[134:137], v[216:219], v[12:15]
	v_mfma_f32_16x16x32_bf16 v[8:11], v[156:159], v[216:219], v[8:11]
	s_setprio 0
	s_setprio 1
	v_mfma_f32_16x16x32_bf16 v[52:55], v[160:163], v[182:185], v[52:55]
	v_mfma_f32_16x16x32_bf16 v[48:51], v[168:171], v[182:185], v[48:51]
	v_mfma_f32_16x16x32_bf16 v[36:39], v[160:163], v[196:199], v[36:39]
	v_mfma_f32_16x16x32_bf16 v[32:35], v[168:171], v[196:199], v[32:35]
	v_mfma_f32_16x16x32_bf16 v[20:23], v[160:163], v[204:207], v[20:23]
	v_mfma_f32_16x16x32_bf16 v[16:19], v[168:171], v[204:207], v[16:19]
	v_mfma_f32_16x16x32_bf16 v[4:7], v[160:163], v[212:215], v[4:7]
	v_mfma_f32_16x16x32_bf16 v[0:3], v[168:171], v[212:215], v[0:3]
	v_mfma_f32_16x16x32_bf16 v[52:55], v[164:167], v[192:195], v[52:55]
	v_mfma_f32_16x16x32_bf16 v[48:51], v[178:181], v[192:195], v[48:51]
	v_mfma_f32_16x16x32_bf16 v[36:39], v[164:167], v[200:203], v[36:39]
	v_mfma_f32_16x16x32_bf16 v[32:35], v[178:181], v[200:203], v[32:35]
	v_mfma_f32_16x16x32_bf16 v[20:23], v[164:167], v[208:211], v[20:23]
	v_mfma_f32_16x16x32_bf16 v[16:19], v[178:181], v[208:211], v[16:19]
	v_mfma_f32_16x16x32_bf16 v[4:7], v[164:167], v[216:219], v[4:7]
	v_mfma_f32_16x16x32_bf16 v[0:3], v[178:181], v[216:219], v[0:3]
	s_setprio 0
	s_barrier
	s_add_i32 s20, 0, 0x18000
	v_add_u32_e32 v128, s20, v174
	s_add_i32 s80, 0, 0x1c000
	ds_read_b128 v[130:133], v128
	ds_read_b128 v[134:137], v128 offset:1024
	ds_read_b128 v[152:155], v128 offset:2048
	ds_read_b128 v[156:159], v128 offset:3072
	v_add_u32_e32 v128, s80, v174
	ds_read_b128 v[160:163], v128
	ds_read_b128 v[164:167], v128 offset:1024
	ds_read_b128 v[168:171], v128 offset:2048
	ds_read_b128 v[178:181], v128 offset:3072
	s_add_u32 s96, s96, 0x80000
	s_addc_u32 s97, s97, 0
	s_mov_b32 m0, s22
	ds_read_b128 v[182:185], v176 offset:32768
	ds_read_b128 v[192:195], v176 offset:33792
	ds_read_b128 v[196:199], v176 offset:34816
	ds_read_b128 v[200:203], v176 offset:35840
	ds_read_b128 v[204:207], v176 offset:36864
	ds_read_b128 v[208:211], v176 offset:37888
	ds_read_b128 v[212:215], v176 offset:38912
	ds_read_b128 v[216:219], v176 offset:39936
	global_load_lds_dwordx4 v138, s[96:97]
	s_mov_b32 m0, s84
	s_nop 0
	global_load_lds_dwordx4 v142, s[96:97]
	s_waitcnt vmcnt(8)
	s_waitcnt lgkmcnt(0)
	s_barrier
	s_setprio 1
	s_waitcnt lgkmcnt(0)
	v_mfma_f32_16x16x32_bf16 v[124:127], v[130:133], v[182:185], v[124:127]
	v_mfma_f32_16x16x32_bf16 v[120:123], v[152:155], v[182:185], v[120:123]
	v_mfma_f32_16x16x32_bf16 v[108:111], v[130:133], v[196:199], v[108:111]
	v_mfma_f32_16x16x32_bf16 v[104:107], v[152:155], v[196:199], v[104:107]
	v_mfma_f32_16x16x32_bf16 v[92:95], v[130:133], v[204:207], v[92:95]
	v_mfma_f32_16x16x32_bf16 v[88:91], v[152:155], v[204:207], v[88:91]
	v_mfma_f32_16x16x32_bf16 v[76:79], v[130:133], v[212:215], v[76:79]
	v_mfma_f32_16x16x32_bf16 v[72:75], v[152:155], v[212:215], v[72:75]
	v_mfma_f32_16x16x32_bf16 v[124:127], v[134:137], v[192:195], v[124:127]
	v_mfma_f32_16x16x32_bf16 v[120:123], v[156:159], v[192:195], v[120:123]
	v_mfma_f32_16x16x32_bf16 v[108:111], v[134:137], v[200:203], v[108:111]
	v_mfma_f32_16x16x32_bf16 v[104:107], v[156:159], v[200:203], v[104:107]
	v_mfma_f32_16x16x32_bf16 v[92:95], v[134:137], v[208:211], v[92:95]
	v_mfma_f32_16x16x32_bf16 v[88:91], v[156:159], v[208:211], v[88:91]
	v_mfma_f32_16x16x32_bf16 v[76:79], v[134:137], v[216:219], v[76:79]
	v_mfma_f32_16x16x32_bf16 v[72:75], v[156:159], v[216:219], v[72:75]
	s_setprio 0
	s_setprio 1
	v_mfma_f32_16x16x32_bf16 v[116:119], v[160:163], v[182:185], v[116:119]
	v_mfma_f32_16x16x32_bf16 v[112:115], v[168:171], v[182:185], v[112:115]
	v_mfma_f32_16x16x32_bf16 v[100:103], v[160:163], v[196:199], v[100:103]
	v_mfma_f32_16x16x32_bf16 v[96:99], v[168:171], v[196:199], v[96:99]
	v_mfma_f32_16x16x32_bf16 v[84:87], v[160:163], v[204:207], v[84:87]
	v_mfma_f32_16x16x32_bf16 v[80:83], v[168:171], v[204:207], v[80:83]
	v_mfma_f32_16x16x32_bf16 v[68:71], v[160:163], v[212:215], v[68:71]
	v_mfma_f32_16x16x32_bf16 v[64:67], v[168:171], v[212:215], v[64:67]
	v_mfma_f32_16x16x32_bf16 v[116:119], v[164:167], v[192:195], v[116:119]
	v_mfma_f32_16x16x32_bf16 v[112:115], v[178:181], v[192:195], v[112:115]
	v_mfma_f32_16x16x32_bf16 v[100:103], v[164:167], v[200:203], v[100:103]
	v_mfma_f32_16x16x32_bf16 v[96:99], v[178:181], v[200:203], v[96:99]
	v_mfma_f32_16x16x32_bf16 v[84:87], v[164:167], v[208:211], v[84:87]
	v_mfma_f32_16x16x32_bf16 v[80:83], v[178:181], v[208:211], v[80:83]
	v_mfma_f32_16x16x32_bf16 v[68:71], v[164:167], v[216:219], v[68:71]
	v_mfma_f32_16x16x32_bf16 v[64:67], v[178:181], v[216:219], v[64:67]
	s_setprio 0
	s_barrier
	s_add_i32 s20, s20, s33
	s_add_u32 s66, s66, 0x80
	s_addc_u32 s67, s67, 0
	s_mov_b32 m0, s20
	ds_read_b128 v[182:185], v176 offset:49152
	ds_read_b128 v[192:195], v176 offset:50176
	ds_read_b128 v[196:199], v176 offset:51200
	ds_read_b128 v[200:203], v176 offset:52224
	ds_read_b128 v[204:207], v176 offset:53248
	ds_read_b128 v[208:211], v176 offset:54272
	ds_read_b128 v[212:215], v176 offset:55296
	ds_read_b128 v[216:219], v176 offset:56320
	global_load_lds_dwordx4 v140, s[66:67]
	s_add_i32 m0, s20, 0x2000
	s_add_i32 s20, s80, s33
	global_load_lds_dwordx4 v144, s[66:67]
	s_add_u32 s66, s66, 0x80000
	s_addc_u32 s67, s67, 0
	s_mov_b32 m0, s20
	s_nop 0
	global_load_lds_dwordx4 v140, s[66:67]
	s_add_i32 m0, s20, 0x2000
	s_nop 0
	global_load_lds_dwordx4 v144, s[66:67]
	s_mov_b32 m0, s45
	s_nop 0
	global_load_lds_dwordx4 v138, s[100:101]
	s_mov_b32 m0, s16
	s_nop 0
	global_load_lds_dwordx4 v142, s[100:101]
	s_waitcnt vmcnt(8)
	s_waitcnt lgkmcnt(0)
	s_barrier
	s_setprio 1
	s_waitcnt lgkmcnt(0)
	v_mfma_f32_16x16x32_bf16 v[60:63], v[130:133], v[182:185], v[60:63]
	v_mfma_f32_16x16x32_bf16 v[56:59], v[152:155], v[182:185], v[56:59]
	v_mfma_f32_16x16x32_bf16 v[44:47], v[130:133], v[196:199], v[44:47]
	v_mfma_f32_16x16x32_bf16 v[40:43], v[152:155], v[196:199], v[40:43]
	v_mfma_f32_16x16x32_bf16 v[28:31], v[130:133], v[204:207], v[28:31]
	v_mfma_f32_16x16x32_bf16 v[24:27], v[152:155], v[204:207], v[24:27]
	v_mfma_f32_16x16x32_bf16 v[12:15], v[130:133], v[212:215], v[12:15]
	v_mfma_f32_16x16x32_bf16 v[8:11], v[152:155], v[212:215], v[8:11]
	v_mfma_f32_16x16x32_bf16 v[60:63], v[134:137], v[192:195], v[60:63]
	v_mfma_f32_16x16x32_bf16 v[56:59], v[156:159], v[192:195], v[56:59]
	v_mfma_f32_16x16x32_bf16 v[44:47], v[134:137], v[200:203], v[44:47]
	v_mfma_f32_16x16x32_bf16 v[40:43], v[156:159], v[200:203], v[40:43]
	v_mfma_f32_16x16x32_bf16 v[28:31], v[134:137], v[208:211], v[28:31]
	v_mfma_f32_16x16x32_bf16 v[24:27], v[156:159], v[208:211], v[24:27]
	v_mfma_f32_16x16x32_bf16 v[12:15], v[134:137], v[216:219], v[12:15]
	v_mfma_f32_16x16x32_bf16 v[8:11], v[156:159], v[216:219], v[8:11]
	s_setprio 0
	s_setprio 1
	v_mfma_f32_16x16x32_bf16 v[52:55], v[160:163], v[182:185], v[52:55]
	v_mfma_f32_16x16x32_bf16 v[48:51], v[168:171], v[182:185], v[48:51]
	v_mfma_f32_16x16x32_bf16 v[36:39], v[160:163], v[196:199], v[36:39]
	v_mfma_f32_16x16x32_bf16 v[32:35], v[168:171], v[196:199], v[32:35]
	v_mfma_f32_16x16x32_bf16 v[20:23], v[160:163], v[204:207], v[20:23]
	v_mfma_f32_16x16x32_bf16 v[16:19], v[168:171], v[204:207], v[16:19]
	v_mfma_f32_16x16x32_bf16 v[4:7], v[160:163], v[212:215], v[4:7]
	v_mfma_f32_16x16x32_bf16 v[0:3], v[168:171], v[212:215], v[0:3]
	v_mfma_f32_16x16x32_bf16 v[52:55], v[164:167], v[192:195], v[52:55]
	v_mfma_f32_16x16x32_bf16 v[48:51], v[178:181], v[192:195], v[48:51]
	v_mfma_f32_16x16x32_bf16 v[36:39], v[164:167], v[200:203], v[36:39]
	v_mfma_f32_16x16x32_bf16 v[32:35], v[178:181], v[200:203], v[32:35]
	v_mfma_f32_16x16x32_bf16 v[20:23], v[164:167], v[208:211], v[20:23]
	v_mfma_f32_16x16x32_bf16 v[16:19], v[178:181], v[208:211], v[16:19]
	v_mfma_f32_16x16x32_bf16 v[4:7], v[164:167], v[216:219], v[4:7]
	v_mfma_f32_16x16x32_bf16 v[0:3], v[178:181], v[216:219], v[0:3]
	s_setprio 0
	s_barrier
	s_add_i32 s90, s90, 2
	s_add_u32 s0, s0, 0x100
	s_addc_u32 s1, s1, 0
	s_add_u32 s59, s59, 0x100
	s_addc_u32 s61, s61, 0
	s_cmp_gt_u32 s90, 29
	s_cbranch_scc0 .LBB0_114
	s_and_b64 vcc, exec, s[56:57]
	s_cbranch_vccz .LBB0_117
	s_barrier

.LBB0_232:
	s_add_u32 s8, s6, 0xfff80080
	s_addc_u32 s9, s7, -1
	s_add_i32 s80, 0, 0x10000
	s_cmp_eq_u32 s20, 28
	s_cselect_b32 s11, s67, s9
	s_cselect_b32 s10, s96, s8
	s_cselect_b32 s9, s65, vcc_hi
	s_cselect_b32 s8, s97, vcc_lo
	s_add_i32 s34, 0, 0x14000
	v_add_u32_e32 v76, s80, v215
	v_add_u32_e32 v158, s34, v215
	ds_read_b128 v[64:67], v76
	ds_read_b128 v[68:71], v76 offset:1024
	ds_read_b128 v[72:75], v76 offset:2048
	ds_read_b128 v[76:79], v76 offset:3072
	ds_read_b128 v[146:149], v158
	ds_read_b128 v[150:153], v158 offset:1024
	ds_read_b128 v[154:157], v158 offset:2048
	ds_read_b128 v[158:161], v158 offset:3072
	s_add_i32 m0, s22, 0xc000
	ds_read_b128 v[162:165], v217
	ds_read_b128 v[166:169], v217 offset:1024
	ds_read_b128 v[170:173], v217 offset:2048
	ds_read_b128 v[174:177], v217 offset:3072
	ds_read_b128 v[194:197], v217 offset:4096
	ds_read_b128 v[198:201], v217 offset:5120
	ds_read_b128 v[202:205], v217 offset:6144
	ds_read_b128 v[206:209], v217 offset:7168
	global_load_lds_dwordx4 v184, s[6:7]
	s_add_i32 m0, s22, 0xe000
	s_nop 0
	global_load_lds_dwordx4 v192, s[6:7]
	s_waitcnt vmcnt(8)
	s_waitcnt lgkmcnt(0)
	s_barrier
	s_setprio 1
	s_waitcnt lgkmcnt(0)
	v_mfma_f32_16x16x32_bf16 v[142:145], v[64:67], v[162:165], v[142:145]
	v_mfma_f32_16x16x32_bf16 v[138:141], v[72:75], v[162:165], v[138:141]
	v_mfma_f32_16x16x32_bf16 v[124:127], v[64:67], v[170:173], v[124:127]
	v_mfma_f32_16x16x32_bf16 v[120:123], v[72:75], v[170:173], v[120:123]
	v_mfma_f32_16x16x32_bf16 v[108:111], v[64:67], v[194:197], v[108:111]
	v_mfma_f32_16x16x32_bf16 v[104:107], v[72:75], v[194:197], v[104:107]
	v_mfma_f32_16x16x32_bf16 v[92:95], v[64:67], v[202:205], v[92:95]
	v_mfma_f32_16x16x32_bf16 v[88:91], v[72:75], v[202:205], v[88:91]
	v_mfma_f32_16x16x32_bf16 v[142:145], v[68:71], v[166:169], v[142:145]
	v_mfma_f32_16x16x32_bf16 v[138:141], v[76:79], v[166:169], v[138:141]
	v_mfma_f32_16x16x32_bf16 v[124:127], v[68:71], v[174:177], v[124:127]
	v_mfma_f32_16x16x32_bf16 v[120:123], v[76:79], v[174:177], v[120:123]
	v_mfma_f32_16x16x32_bf16 v[108:111], v[68:71], v[198:201], v[108:111]
	v_mfma_f32_16x16x32_bf16 v[104:107], v[76:79], v[198:201], v[104:107]
	v_mfma_f32_16x16x32_bf16 v[92:95], v[68:71], v[206:209], v[92:95]
	v_mfma_f32_16x16x32_bf16 v[88:91], v[76:79], v[206:209], v[88:91]
	s_setprio 0
	s_setprio 1
	v_mfma_f32_16x16x32_bf16 v[134:137], v[146:149], v[162:165], v[134:137]
	v_mfma_f32_16x16x32_bf16 v[130:133], v[154:157], v[162:165], v[130:133]
	v_mfma_f32_16x16x32_bf16 v[116:119], v[146:149], v[170:173], v[116:119]
	v_mfma_f32_16x16x32_bf16 v[112:115], v[154:157], v[170:173], v[112:115]
	v_mfma_f32_16x16x32_bf16 v[100:103], v[146:149], v[194:197], v[100:103]
	v_mfma_f32_16x16x32_bf16 v[96:99], v[154:157], v[194:197], v[96:99]
	v_mfma_f32_16x16x32_bf16 v[84:87], v[146:149], v[202:205], v[84:87]
	v_mfma_f32_16x16x32_bf16 v[80:83], v[154:157], v[202:205], v[80:83]
	v_mfma_f32_16x16x32_bf16 v[134:137], v[150:153], v[166:169], v[134:137]
	v_mfma_f32_16x16x32_bf16 v[130:133], v[158:161], v[166:169], v[130:133]
	v_mfma_f32_16x16x32_bf16 v[116:119], v[150:153], v[174:177], v[116:119]
	v_mfma_f32_16x16x32_bf16 v[112:115], v[158:161], v[174:177], v[112:115]
	v_mfma_f32_16x16x32_bf16 v[100:103], v[150:153], v[198:201], v[100:103]
	v_mfma_f32_16x16x32_bf16 v[96:99], v[158:161], v[198:201], v[96:99]
	v_mfma_f32_16x16x32_bf16 v[84:87], v[150:153], v[206:209], v[84:87]
	v_mfma_f32_16x16x32_bf16 v[80:83], v[158:161], v[206:209], v[80:83]
	s_setprio 0
	s_barrier
	s_add_i32 s35, s80, s21
	s_mov_b32 m0, s35
	ds_read_b128 v[162:165], v217 offset:16384
	ds_read_b128 v[166:169], v217 offset:17408
	ds_read_b128 v[170:173], v217 offset:18432
	ds_read_b128 v[174:177], v217 offset:19456
	ds_read_b128 v[194:197], v217 offset:20480
	ds_read_b128 v[198:201], v217 offset:21504
	ds_read_b128 v[202:205], v217 offset:22528
	ds_read_b128 v[206:209], v217 offset:23552
	global_load_lds_dwordx4 v128, s[8:9]
	s_add_i32 m0, s35, 0x2000
	s_add_u32 s80, s8, 0x80000
	s_addc_u32 s81, s9, 0
	s_add_i32 s34, s34, s21
	global_load_lds_dwordx4 v178, s[8:9]
	s_mov_b32 m0, s34
	s_nop 0
	global_load_lds_dwordx4 v128, s[80:81]
	s_add_i32 m0, s34, 0x2000
	s_nop 0
	global_load_lds_dwordx4 v178, s[80:81]
	s_mov_b32 m0, s22
	s_nop 0
	global_load_lds_dwordx4 v182, s[10:11]
	s_mov_b32 m0, s23
	s_nop 0
	global_load_lds_dwordx4 v180, s[10:11]
	s_add_u32 s100, s10, 0x80
	s_addc_u32 s101, s11, 0
	s_waitcnt vmcnt(8)
	s_waitcnt lgkmcnt(0)
	s_barrier
	s_setprio 1
	s_waitcnt lgkmcnt(0)
	v_mfma_f32_16x16x32_bf16 v[60:63], v[64:67], v[162:165], v[60:63]
	v_mfma_f32_16x16x32_bf16 v[56:59], v[72:75], v[162:165], v[56:59]
	v_mfma_f32_16x16x32_bf16 v[44:47], v[64:67], v[170:173], v[44:47]
	v_mfma_f32_16x16x32_bf16 v[40:43], v[72:75], v[170:173], v[40:43]
	v_mfma_f32_16x16x32_bf16 v[28:31], v[64:67], v[194:197], v[28:31]
	v_mfma_f32_16x16x32_bf16 v[24:27], v[72:75], v[194:197], v[24:27]
	v_mfma_f32_16x16x32_bf16 v[12:15], v[64:67], v[202:205], v[12:15]
	v_mfma_f32_16x16x32_bf16 v[8:11], v[72:75], v[202:205], v[8:11]
	v_mfma_f32_16x16x32_bf16 v[60:63], v[68:71], v[166:169], v[60:63]
	v_mfma_f32_16x16x32_bf16 v[56:59], v[76:79], v[166:169], v[56:59]
	v_mfma_f32_16x16x32_bf16 v[44:47], v[68:71], v[174:177], v[44:47]
	v_mfma_f32_16x16x32_bf16 v[40:43], v[76:79], v[174:177], v[40:43]
	v_mfma_f32_16x16x32_bf16 v[28:31], v[68:71], v[198:201], v[28:31]
	v_mfma_f32_16x16x32_bf16 v[24:27], v[76:79], v[198:201], v[24:27]
	v_mfma_f32_16x16x32_bf16 v[12:15], v[68:71], v[206:209], v[12:15]
	v_mfma_f32_16x16x32_bf16 v[8:11], v[76:79], v[206:209], v[8:11]
	s_setprio 0
	s_setprio 1
	v_mfma_f32_16x16x32_bf16 v[52:55], v[146:149], v[162:165], v[52:55]
	v_mfma_f32_16x16x32_bf16 v[48:51], v[154:157], v[162:165], v[48:51]
	v_mfma_f32_16x16x32_bf16 v[36:39], v[146:149], v[170:173], v[36:39]
	v_mfma_f32_16x16x32_bf16 v[32:35], v[154:157], v[170:173], v[32:35]
	v_mfma_f32_16x16x32_bf16 v[20:23], v[146:149], v[194:197], v[20:23]
	v_mfma_f32_16x16x32_bf16 v[16:19], v[154:157], v[194:197], v[16:19]
	v_mfma_f32_16x16x32_bf16 v[4:7], v[146:149], v[202:205], v[4:7]
	v_mfma_f32_16x16x32_bf16 v[0:3], v[154:157], v[202:205], v[0:3]
	v_mfma_f32_16x16x32_bf16 v[52:55], v[150:153], v[166:169], v[52:55]
	v_mfma_f32_16x16x32_bf16 v[48:51], v[158:161], v[166:169], v[48:51]
	v_mfma_f32_16x16x32_bf16 v[36:39], v[150:153], v[174:177], v[36:39]
	v_mfma_f32_16x16x32_bf16 v[32:35], v[158:161], v[174:177], v[32:35]
	v_mfma_f32_16x16x32_bf16 v[20:23], v[150:153], v[198:201], v[20:23]
	v_mfma_f32_16x16x32_bf16 v[16:19], v[158:161], v[198:201], v[16:19]
	v_mfma_f32_16x16x32_bf16 v[4:7], v[150:153], v[206:209], v[4:7]
	v_mfma_f32_16x16x32_bf16 v[0:3], v[158:161], v[206:209], v[0:3]
	s_setprio 0
	s_barrier
	s_add_i32 s34, 0, 0x18000
	s_add_i32 s35, 0, 0x1c000
	v_add_u32_e32 v76, s34, v215
	v_add_u32_e32 v158, s35, v215
	ds_read_b128 v[64:67], v76
	ds_read_b128 v[68:71], v76 offset:1024
	ds_read_b128 v[72:75], v76 offset:2048
	ds_read_b128 v[76:79], v76 offset:3072
	ds_read_b128 v[146:149], v158
	ds_read_b128 v[150:153], v158 offset:1024
	ds_read_b128 v[154:157], v158 offset:2048
	ds_read_b128 v[158:161], v158 offset:3072
	s_add_u32 s10, s10, 0x80000
	s_addc_u32 s11, s11, 0
	s_mov_b32 m0, s33
	ds_read_b128 v[162:165], v217 offset:32768
	ds_read_b128 v[166:169], v217 offset:33792
	ds_read_b128 v[170:173], v217 offset:34816
	ds_read_b128 v[174:177], v217 offset:35840
	ds_read_b128 v[194:197], v217 offset:36864
	ds_read_b128 v[198:201], v217 offset:37888
	ds_read_b128 v[202:205], v217 offset:38912
	ds_read_b128 v[206:209], v217 offset:39936
	global_load_lds_dwordx4 v182, s[10:11]
	s_mov_b32 m0, s44
	s_nop 0
	global_load_lds_dwordx4 v180, s[10:11]
	s_waitcnt vmcnt(8)
	s_waitcnt lgkmcnt(0)
	s_barrier
	s_setprio 1
	s_waitcnt lgkmcnt(0)
	v_mfma_f32_16x16x32_bf16 v[142:145], v[64:67], v[162:165], v[142:145]
	v_mfma_f32_16x16x32_bf16 v[138:141], v[72:75], v[162:165], v[138:141]
	v_mfma_f32_16x16x32_bf16 v[124:127], v[64:67], v[170:173], v[124:127]
	v_mfma_f32_16x16x32_bf16 v[120:123], v[72:75], v[170:173], v[120:123]
	v_mfma_f32_16x16x32_bf16 v[108:111], v[64:67], v[194:197], v[108:111]
	v_mfma_f32_16x16x32_bf16 v[104:107], v[72:75], v[194:197], v[104:107]
	v_mfma_f32_16x16x32_bf16 v[92:95], v[64:67], v[202:205], v[92:95]
	v_mfma_f32_16x16x32_bf16 v[88:91], v[72:75], v[202:205], v[88:91]
	v_mfma_f32_16x16x32_bf16 v[142:145], v[68:71], v[166:169], v[142:145]
	v_mfma_f32_16x16x32_bf16 v[138:141], v[76:79], v[166:169], v[138:141]
	v_mfma_f32_16x16x32_bf16 v[124:127], v[68:71], v[174:177], v[124:127]
	v_mfma_f32_16x16x32_bf16 v[120:123], v[76:79], v[174:177], v[120:123]
	v_mfma_f32_16x16x32_bf16 v[108:111], v[68:71], v[198:201], v[108:111]
	v_mfma_f32_16x16x32_bf16 v[104:107], v[76:79], v[198:201], v[104:107]
	v_mfma_f32_16x16x32_bf16 v[92:95], v[68:71], v[206:209], v[92:95]
	v_mfma_f32_16x16x32_bf16 v[88:91], v[76:79], v[206:209], v[88:91]
	s_setprio 0
	s_setprio 1
	v_mfma_f32_16x16x32_bf16 v[134:137], v[146:149], v[162:165], v[134:137]
	v_mfma_f32_16x16x32_bf16 v[130:133], v[154:157], v[162:165], v[130:133]
	v_mfma_f32_16x16x32_bf16 v[116:119], v[146:149], v[170:173], v[116:119]
	v_mfma_f32_16x16x32_bf16 v[112:115], v[154:157], v[170:173], v[112:115]
	v_mfma_f32_16x16x32_bf16 v[100:103], v[146:149], v[194:197], v[100:103]
	v_mfma_f32_16x16x32_bf16 v[96:99], v[154:157], v[194:197], v[96:99]
	v_mfma_f32_16x16x32_bf16 v[84:87], v[146:149], v[202:205], v[84:87]
	v_mfma_f32_16x16x32_bf16 v[80:83], v[154:157], v[202:205], v[80:83]
	v_mfma_f32_16x16x32_bf16 v[134:137], v[150:153], v[166:169], v[134:137]
	v_mfma_f32_16x16x32_bf16 v[130:133], v[158:161], v[166:169], v[130:133]
	v_mfma_f32_16x16x32_bf16 v[116:119], v[150:153], v[174:177], v[116:119]
	v_mfma_f32_16x16x32_bf16 v[112:115], v[158:161], v[174:177], v[112:115]
	v_mfma_f32_16x16x32_bf16 v[100:103], v[150:153], v[198:201], v[100:103]
	v_mfma_f32_16x16x32_bf16 v[96:99], v[158:161], v[198:201], v[96:99]
	v_mfma_f32_16x16x32_bf16 v[84:87], v[150:153], v[206:209], v[84:87]
	v_mfma_f32_16x16x32_bf16 v[80:83], v[158:161], v[206:209], v[80:83]
	s_setprio 0
	s_barrier
	s_add_i32 s10, s34, s21
	s_add_u32 s8, s8, 0x80
	s_addc_u32 s9, s9, 0
	s_mov_b32 m0, s10
	ds_read_b128 v[162:165], v217 offset:49152
	ds_read_b128 v[166:169], v217 offset:50176
	ds_read_b128 v[170:173], v217 offset:51200
	ds_read_b128 v[174:177], v217 offset:52224
	ds_read_b128 v[194:197], v217 offset:53248
	ds_read_b128 v[198:201], v217 offset:54272
	ds_read_b128 v[202:205], v217 offset:55296
	ds_read_b128 v[206:209], v217 offset:56320
	global_load_lds_dwordx4 v128, s[8:9]
	s_add_i32 m0, s10, 0x2000
	s_add_i32 s10, s35, s21
	global_load_lds_dwordx4 v178, s[8:9]
	s_add_u32 s8, s8, 0x80000
	s_addc_u32 s9, s9, 0
	s_mov_b32 m0, s10
	s_nop 0
	global_load_lds_dwordx4 v128, s[8:9]
	s_add_i32 m0, s10, 0x2000
	s_nop 0
	global_load_lds_dwordx4 v178, s[8:9]
	s_mov_b32 m0, s1
	s_nop 0
	global_load_lds_dwordx4 v182, s[100:101]
	s_mov_b32 m0, s3
	s_nop 0
	global_load_lds_dwordx4 v180, s[100:101]
	s_waitcnt vmcnt(8)
	s_waitcnt lgkmcnt(0)
	s_barrier
	s_setprio 1
	s_waitcnt lgkmcnt(0)
	v_mfma_f32_16x16x32_bf16 v[60:63], v[64:67], v[162:165], v[60:63]
	v_mfma_f32_16x16x32_bf16 v[56:59], v[72:75], v[162:165], v[56:59]
	v_mfma_f32_16x16x32_bf16 v[44:47], v[64:67], v[170:173], v[44:47]
	v_mfma_f32_16x16x32_bf16 v[40:43], v[72:75], v[170:173], v[40:43]
	v_mfma_f32_16x16x32_bf16 v[28:31], v[64:67], v[194:197], v[28:31]
	v_mfma_f32_16x16x32_bf16 v[24:27], v[72:75], v[194:197], v[24:27]
	v_mfma_f32_16x16x32_bf16 v[12:15], v[64:67], v[202:205], v[12:15]
	v_mfma_f32_16x16x32_bf16 v[8:11], v[72:75], v[202:205], v[8:11]
	v_mfma_f32_16x16x32_bf16 v[60:63], v[68:71], v[166:169], v[60:63]
	v_mfma_f32_16x16x32_bf16 v[56:59], v[76:79], v[166:169], v[56:59]
	v_mfma_f32_16x16x32_bf16 v[44:47], v[68:71], v[174:177], v[44:47]
	v_mfma_f32_16x16x32_bf16 v[40:43], v[76:79], v[174:177], v[40:43]
	v_mfma_f32_16x16x32_bf16 v[28:31], v[68:71], v[198:201], v[28:31]
	v_mfma_f32_16x16x32_bf16 v[24:27], v[76:79], v[198:201], v[24:27]
	v_mfma_f32_16x16x32_bf16 v[12:15], v[68:71], v[206:209], v[12:15]
	v_mfma_f32_16x16x32_bf16 v[8:11], v[76:79], v[206:209], v[8:11]
	s_setprio 0
	s_setprio 1
	v_mfma_f32_16x16x32_bf16 v[52:55], v[146:149], v[162:165], v[52:55]
	v_mfma_f32_16x16x32_bf16 v[48:51], v[154:157], v[162:165], v[48:51]
	v_mfma_f32_16x16x32_bf16 v[36:39], v[146:149], v[170:173], v[36:39]
	v_mfma_f32_16x16x32_bf16 v[32:35], v[154:157], v[170:173], v[32:35]
	v_mfma_f32_16x16x32_bf16 v[20:23], v[146:149], v[194:197], v[20:23]
	v_mfma_f32_16x16x32_bf16 v[16:19], v[154:157], v[194:197], v[16:19]
	v_mfma_f32_16x16x32_bf16 v[4:7], v[146:149], v[202:205], v[4:7]
	v_mfma_f32_16x16x32_bf16 v[0:3], v[154:157], v[202:205], v[0:3]
	v_mfma_f32_16x16x32_bf16 v[52:55], v[150:153], v[166:169], v[52:55]
	v_mfma_f32_16x16x32_bf16 v[48:51], v[158:161], v[166:169], v[48:51]
	v_mfma_f32_16x16x32_bf16 v[36:39], v[150:153], v[174:177], v[36:39]
	v_mfma_f32_16x16x32_bf16 v[32:35], v[158:161], v[174:177], v[32:35]
	v_mfma_f32_16x16x32_bf16 v[20:23], v[150:153], v[198:201], v[20:23]
	v_mfma_f32_16x16x32_bf16 v[16:19], v[158:161], v[198:201], v[16:19]
	v_mfma_f32_16x16x32_bf16 v[4:7], v[150:153], v[206:209], v[4:7]
	v_mfma_f32_16x16x32_bf16 v[0:3], v[158:161], v[206:209], v[0:3]
	s_setprio 0
	s_barrier
	s_add_i32 s20, s20, 2
	s_add_u32 s6, s6, 0x100
	s_addc_u32 s7, s7, 0
	s_add_u32 vcc_lo, vcc_lo, 0x100
	s_addc_u32 vcc_hi, vcc_hi, 0
	s_cmp_gt_u32 s20, 29
	s_cbranch_scc0 .LBB0_232
	s_and_b64 vcc, exec, s[60:61]
	s_cbranch_vccz .LBB0_235
	s_barrier

	.amdhsa_kernel _Z8mega_fwd6Paramsiii
		.amdhsa_group_segment_fixed_size 0
		.amdhsa_private_segment_fixed_size 0
		.amdhsa_kernarg_size 456
		.amdhsa_user_sgpr_count 2
		.amdhsa_user_sgpr_dispatch_ptr 0
		.amdhsa_user_sgpr_queue_ptr 0
		.amdhsa_user_sgpr_kernarg_segment_ptr 1
		.amdhsa_user_sgpr_dispatch_id 0
		.amdhsa_user_sgpr_kernarg_preload_length 0
		.amdhsa_user_sgpr_kernarg_preload_offset 0
		.amdhsa_user_sgpr_private_segment_size 0
		.amdhsa_uses_dynamic_stack 0
		.amdhsa_enable_private_segment 0
		.amdhsa_system_sgpr_workgroup_id_x 1
		.amdhsa_system_sgpr_workgroup_id_y 0
		.amdhsa_system_sgpr_workgroup_id_z 0
		.amdhsa_system_sgpr_workgroup_info 0
		.amdhsa_system_vgpr_workitem_id 2
		.amdhsa_next_free_vgpr 256
		.amdhsa_next_free_sgpr 102
		.amdhsa_accum_offset 256
		.amdhsa_reserve_vcc 1
		.amdhsa_float_round_mode_32 0
		.amdhsa_float_round_mode_16_64 0
		.amdhsa_float_denorm_mode_32 3
		.amdhsa_float_denorm_mode_16_64 3
		.amdhsa_dx10_clamp 1
		.amdhsa_ieee_mode 1
		.amdhsa_fp16_overflow 0
		.amdhsa_tg_split 0
		.amdhsa_exception_fp_ieee_invalid_op 0
		.amdhsa_exception_fp_denorm_src 0
		.amdhsa_exception_fp_ieee_div_zero 0
		.amdhsa_exception_fp_ieee_overflow 0
		.amdhsa_exception_fp_ieee_underflow 0
		.amdhsa_exception_fp_ieee_inexact 0
		.amdhsa_exception_int_div_zero 0
	.end_amdhsa_kernel

amdhsa.kernels:
  - .agpr_count:     0
    .args:
      - .offset:         0
        .size:           184
        .value_kind:     by_value
      - .offset:         184
        .size:           4
        .value_kind:     by_value
      - .offset:         188
        .size:           4
        .value_kind:     by_value
      - .offset:         192
        .size:           4
        .value_kind:     by_value
      - .offset:         200
        .size:           4
        .value_kind:     hidden_block_count_x
      - .offset:         204
        .size:           4
        .value_kind:     hidden_block_count_y
      - .offset:         208
        .size:           4
        .value_kind:     hidden_block_count_z
      - .offset:         212
        .size:           2
        .value_kind:     hidden_group_size_x
      - .offset:         214
        .size:           2
        .value_kind:     hidden_group_size_y
      - .offset:         216
        .size:           2
        .value_kind:     hidden_group_size_z
      - .offset:         218
        .size:           2
        .value_kind:     hidden_remainder_x
      - .offset:         220
        .size:           2
        .value_kind:     hidden_remainder_y
      - .offset:         222
        .size:           2
        .value_kind:     hidden_remainder_z
      - .offset:         240
        .size:           8
        .value_kind:     hidden_global_offset_x
      - .offset:         248
        .size:           8
        .value_kind:     hidden_global_offset_y
      - .offset:         256
        .size:           8
        .value_kind:     hidden_global_offset_z
      - .offset:         264
        .size:           2
        .value_kind:     hidden_grid_dims
      - .offset:         288
        .size:           8
        .value_kind:     hidden_multigrid_sync_arg
      - .offset:         320
        .size:           4
        .value_kind:     hidden_dynamic_lds_size
    .group_segment_fixed_size: 0
    .kernarg_segment_align: 8
    .kernarg_segment_size: 456
    .language:       OpenCL C
    .language_version:
      - 2
      - 0
    .max_flat_workgroup_size: 512
    .name:           _Z8mega_fwd6Paramsiii
    .private_segment_fixed_size: 0
    .sgpr_count:     108
    .sgpr_spill_count: 271
    .symbol:         _Z8mega_fwd6Paramsiii.kd
    .uniform_work_group_size: 1
    .uses_dynamic_stack: false
    .vgpr_count:     256
    .vgpr_spill_count: 0
    .wavefront_size: 64
